# combination 2: HGRN scan with all segments' loads issued up front + attention barrier moves/single fp32 ops + pass-1 row loads via LDS + rotary prefetch + K-loop rotation
# speedup vs baseline: 1.0159x; 1.0086x over previous
.LBB0_420:
	v_ashrrev_i32_e32 v0, 15, v10
	v_cmp_gt_i32_e32 vcc, 2, v0
	v_lshlrev_b32_e32 v2, 4, v0
	v_lshl_add_u32 v0, v0, 2, 24
	v_and_b32_e32 v4, 0xfff, v10
	v_cndmask_b32_e32 v13, v0, v2, vcc
	v_and_b32_e32 v0, 0x1000, v10
	v_cndmask_b32_e64 v12, 4, 16, vcc
	v_cmp_eq_u32_e32 vcc, 0, v0
	v_lshlrev_b32_e32 v0, 4, v4
	v_lshl_add_u64 v[2:3], s[8:9], 0, v[0:1]
	v_lshlrev_b32_e32 v0, 3, v4
	v_bfe_u32 v11, v10, 5, 7
	v_bfe_u32 v14, v10, 12, 3
	v_lshl_add_u64 v[4:5], s[22:23], 0, v[0:1]
	v_add_u32_e32 v0, -1, v13
	s_mov_b64 s[14:15], exec
	v_mov_b32_e32 v6, 0
	v_mov_b32_e32 v7, v1
	v_mov_b32_e32 v8, 0
	v_mov_b32_e32 v9, v1
	v_add_u32_e32 v28, -1, v12
	v_mov_b32_e32 v19, 0
	v_min_u32_e32 v15, 0, v28
	v_sub_u32_e32 v16, v12, v15
	v_add_u32_e32 v16, v0, v16
	v_add_u32_e32 v17, v13, v15
	v_cndmask_b32_e32 v16, v16, v17, vcc
	v_lshl_or_b32 v128, v16, 3, v14
	v_lshlrev_b32_e32 v18, 16, v128
	v_lshl_add_u64 v[22:23], v[2:3], 0, v[18:19]
	global_load_dwordx4 v[32:35], v[22:23], off
	v_lshl_or_b32 v18, v128, 7, v11
	v_lshl_add_u64 v[26:27], v[18:19], 2, s[10:11]
	global_load_dword v96, v[26:27], off
	v_min_u32_e32 v15, 1, v28
	v_sub_u32_e32 v16, v12, v15
	v_add_u32_e32 v16, v0, v16
	v_add_u32_e32 v17, v13, v15
	v_cndmask_b32_e32 v16, v16, v17, vcc
	v_lshl_or_b32 v129, v16, 3, v14
	v_lshlrev_b32_e32 v18, 16, v129
	v_lshl_add_u64 v[22:23], v[2:3], 0, v[18:19]
	global_load_dwordx4 v[36:39], v[22:23], off
	v_lshl_or_b32 v18, v129, 7, v11
	v_lshl_add_u64 v[26:27], v[18:19], 2, s[10:11]
	global_load_dword v98, v[26:27], off
	v_min_u32_e32 v15, 2, v28
	v_sub_u32_e32 v16, v12, v15
	v_add_u32_e32 v16, v0, v16
	v_add_u32_e32 v17, v13, v15
	v_cndmask_b32_e32 v16, v16, v17, vcc
	v_lshl_or_b32 v130, v16, 3, v14
	v_lshlrev_b32_e32 v18, 16, v130
	v_lshl_add_u64 v[22:23], v[2:3], 0, v[18:19]
	global_load_dwordx4 v[40:43], v[22:23], off
	v_lshl_or_b32 v18, v130, 7, v11
	v_lshl_add_u64 v[26:27], v[18:19], 2, s[10:11]
	global_load_dword v100, v[26:27], off
	v_min_u32_e32 v15, 3, v28
	v_sub_u32_e32 v16, v12, v15
	v_add_u32_e32 v16, v0, v16
	v_add_u32_e32 v17, v13, v15
	v_cndmask_b32_e32 v16, v16, v17, vcc
	v_lshl_or_b32 v131, v16, 3, v14
	v_lshlrev_b32_e32 v18, 16, v131
	v_lshl_add_u64 v[22:23], v[2:3], 0, v[18:19]
	global_load_dwordx4 v[44:47], v[22:23], off
	v_lshl_or_b32 v18, v131, 7, v11
	v_lshl_add_u64 v[26:27], v[18:19], 2, s[10:11]
	global_load_dword v102, v[26:27], off
	v_min_u32_e32 v15, 4, v28
	v_sub_u32_e32 v16, v12, v15
	v_add_u32_e32 v16, v0, v16
	v_add_u32_e32 v17, v13, v15
	v_cndmask_b32_e32 v16, v16, v17, vcc
	v_lshl_or_b32 v132, v16, 3, v14
	v_lshlrev_b32_e32 v18, 16, v132
	v_lshl_add_u64 v[22:23], v[2:3], 0, v[18:19]
	global_load_dwordx4 v[48:51], v[22:23], off
	v_lshl_or_b32 v18, v132, 7, v11
	v_lshl_add_u64 v[26:27], v[18:19], 2, s[10:11]
	global_load_dword v104, v[26:27], off
	v_min_u32_e32 v15, 5, v28
	v_sub_u32_e32 v16, v12, v15
	v_add_u32_e32 v16, v0, v16
	v_add_u32_e32 v17, v13, v15
	v_cndmask_b32_e32 v16, v16, v17, vcc
	v_lshl_or_b32 v133, v16, 3, v14
	v_lshlrev_b32_e32 v18, 16, v133
	v_lshl_add_u64 v[22:23], v[2:3], 0, v[18:19]
	global_load_dwordx4 v[52:55], v[22:23], off
	v_lshl_or_b32 v18, v133, 7, v11
	v_lshl_add_u64 v[26:27], v[18:19], 2, s[10:11]
	global_load_dword v106, v[26:27], off
	v_min_u32_e32 v15, 6, v28
	v_sub_u32_e32 v16, v12, v15
	v_add_u32_e32 v16, v0, v16
	v_add_u32_e32 v17, v13, v15
	v_cndmask_b32_e32 v16, v16, v17, vcc
	v_lshl_or_b32 v134, v16, 3, v14
	v_lshlrev_b32_e32 v18, 16, v134
	v_lshl_add_u64 v[22:23], v[2:3], 0, v[18:19]
	global_load_dwordx4 v[56:59], v[22:23], off
	v_lshl_or_b32 v18, v134, 7, v11
	v_lshl_add_u64 v[26:27], v[18:19], 2, s[10:11]
	global_load_dword v108, v[26:27], off
	v_min_u32_e32 v15, 7, v28
	v_sub_u32_e32 v16, v12, v15
	v_add_u32_e32 v16, v0, v16
	v_add_u32_e32 v17, v13, v15
	v_cndmask_b32_e32 v16, v16, v17, vcc
	v_lshl_or_b32 v135, v16, 3, v14
	v_lshlrev_b32_e32 v18, 16, v135
	v_lshl_add_u64 v[22:23], v[2:3], 0, v[18:19]
	global_load_dwordx4 v[60:63], v[22:23], off
	v_lshl_or_b32 v18, v135, 7, v11
	v_lshl_add_u64 v[26:27], v[18:19], 2, s[10:11]
	global_load_dword v110, v[26:27], off
	v_min_u32_e32 v15, 8, v28
	v_sub_u32_e32 v16, v12, v15
	v_add_u32_e32 v16, v0, v16
	v_add_u32_e32 v17, v13, v15
	v_cndmask_b32_e32 v16, v16, v17, vcc
	v_lshl_or_b32 v136, v16, 3, v14
	v_lshlrev_b32_e32 v18, 16, v136
	v_lshl_add_u64 v[22:23], v[2:3], 0, v[18:19]
	global_load_dwordx4 v[64:67], v[22:23], off
	v_lshl_or_b32 v18, v136, 7, v11
	v_lshl_add_u64 v[26:27], v[18:19], 2, s[10:11]
	global_load_dword v112, v[26:27], off
	v_min_u32_e32 v15, 9, v28
	v_sub_u32_e32 v16, v12, v15
	v_add_u32_e32 v16, v0, v16
	v_add_u32_e32 v17, v13, v15
	v_cndmask_b32_e32 v16, v16, v17, vcc
	v_lshl_or_b32 v137, v16, 3, v14
	v_lshlrev_b32_e32 v18, 16, v137
	v_lshl_add_u64 v[22:23], v[2:3], 0, v[18:19]
	global_load_dwordx4 v[68:71], v[22:23], off
	v_lshl_or_b32 v18, v137, 7, v11
	v_lshl_add_u64 v[26:27], v[18:19], 2, s[10:11]
	global_load_dword v114, v[26:27], off
	v_min_u32_e32 v15, 10, v28
	v_sub_u32_e32 v16, v12, v15
	v_add_u32_e32 v16, v0, v16
	v_add_u32_e32 v17, v13, v15
	v_cndmask_b32_e32 v16, v16, v17, vcc
	v_lshl_or_b32 v138, v16, 3, v14
	v_lshlrev_b32_e32 v18, 16, v138
	v_lshl_add_u64 v[22:23], v[2:3], 0, v[18:19]
	global_load_dwordx4 v[72:75], v[22:23], off
	v_lshl_or_b32 v18, v138, 7, v11
	v_lshl_add_u64 v[26:27], v[18:19], 2, s[10:11]
	global_load_dword v116, v[26:27], off
	v_min_u32_e32 v15, 11, v28
	v_sub_u32_e32 v16, v12, v15
	v_add_u32_e32 v16, v0, v16
	v_add_u32_e32 v17, v13, v15
	v_cndmask_b32_e32 v16, v16, v17, vcc
	v_lshl_or_b32 v139, v16, 3, v14
	v_lshlrev_b32_e32 v18, 16, v139
	v_lshl_add_u64 v[22:23], v[2:3], 0, v[18:19]
	global_load_dwordx4 v[76:79], v[22:23], off
	v_lshl_or_b32 v18, v139, 7, v11
	v_lshl_add_u64 v[26:27], v[18:19], 2, s[10:11]
	global_load_dword v118, v[26:27], off
	v_min_u32_e32 v15, 12, v28
	v_sub_u32_e32 v16, v12, v15
	v_add_u32_e32 v16, v0, v16
	v_add_u32_e32 v17, v13, v15
	v_cndmask_b32_e32 v16, v16, v17, vcc
	v_lshl_or_b32 v140, v16, 3, v14
	v_lshlrev_b32_e32 v18, 16, v140
	v_lshl_add_u64 v[22:23], v[2:3], 0, v[18:19]
	global_load_dwordx4 v[80:83], v[22:23], off
	v_lshl_or_b32 v18, v140, 7, v11
	v_lshl_add_u64 v[26:27], v[18:19], 2, s[10:11]
	global_load_dword v120, v[26:27], off
	v_min_u32_e32 v15, 13, v28
	v_sub_u32_e32 v16, v12, v15
	v_add_u32_e32 v16, v0, v16
	v_add_u32_e32 v17, v13, v15
	v_cndmask_b32_e32 v16, v16, v17, vcc
	v_lshl_or_b32 v141, v16, 3, v14
	v_lshlrev_b32_e32 v18, 16, v141
	v_lshl_add_u64 v[22:23], v[2:3], 0, v[18:19]
	global_load_dwordx4 v[84:87], v[22:23], off
	v_lshl_or_b32 v18, v141, 7, v11
	v_lshl_add_u64 v[26:27], v[18:19], 2, s[10:11]
	global_load_dword v122, v[26:27], off
	v_min_u32_e32 v15, 14, v28
	v_sub_u32_e32 v16, v12, v15
	v_add_u32_e32 v16, v0, v16
	v_add_u32_e32 v17, v13, v15
	v_cndmask_b32_e32 v16, v16, v17, vcc
	v_lshl_or_b32 v142, v16, 3, v14
	v_lshlrev_b32_e32 v18, 16, v142
	v_lshl_add_u64 v[22:23], v[2:3], 0, v[18:19]
	global_load_dwordx4 v[88:91], v[22:23], off
	v_lshl_or_b32 v18, v142, 7, v11
	v_lshl_add_u64 v[26:27], v[18:19], 2, s[10:11]
	global_load_dword v124, v[26:27], off
	v_min_u32_e32 v15, 15, v28
	v_sub_u32_e32 v16, v12, v15
	v_add_u32_e32 v16, v0, v16
	v_add_u32_e32 v17, v13, v15
	v_cndmask_b32_e32 v16, v16, v17, vcc
	v_lshl_or_b32 v143, v16, 3, v14
	v_lshlrev_b32_e32 v18, 16, v143
	v_lshl_add_u64 v[22:23], v[2:3], 0, v[18:19]
	global_load_dwordx4 v[92:95], v[22:23], off
	v_lshl_or_b32 v18, v143, 7, v11
	v_lshl_add_u64 v[26:27], v[18:19], 2, s[10:11]
	global_load_dword v126, v[26:27], off
	v_mov_b32_e32 v17, 0
	v_lshlrev_b32_e32 v16, 15, v128
	v_lshl_add_u64 v[24:25], v[4:5], 0, v[16:17]
	v_cvt_pk_bf16_f32 v20, v6, v7
	v_cvt_pk_bf16_f32 v21, v8, v9
	global_store_dwordx2 v[24:25], v[20:21], off
	s_waitcnt vmcnt(31)
	v_pk_fma_f32 v[8:9], v[8:9], v[96:97], v[34:35] op_sel_hi:[1,0,1]
	v_pk_fma_f32 v[6:7], v[6:7], v[96:97], v[32:33] op_sel_hi:[1,0,1]
	v_cmp_gt_u32_e64 s[4:5], v12, 1
	s_and_b64 exec, exec, s[4:5]
	s_cbranch_execz .Lscan_end
	v_lshlrev_b32_e32 v16, 15, v129
	v_lshl_add_u64 v[24:25], v[4:5], 0, v[16:17]
	v_cvt_pk_bf16_f32 v20, v6, v7
	v_cvt_pk_bf16_f32 v21, v8, v9
	global_store_dwordx2 v[24:25], v[20:21], off
	s_waitcnt vmcnt(30)
	v_pk_fma_f32 v[8:9], v[8:9], v[98:99], v[38:39] op_sel_hi:[1,0,1]
	v_pk_fma_f32 v[6:7], v[6:7], v[98:99], v[36:37] op_sel_hi:[1,0,1]
	v_cmp_gt_u32_e64 s[4:5], v12, 2
	s_and_b64 exec, exec, s[4:5]
	s_cbranch_execz .Lscan_end
	v_lshlrev_b32_e32 v16, 15, v130
	v_lshl_add_u64 v[24:25], v[4:5], 0, v[16:17]
	v_cvt_pk_bf16_f32 v20, v6, v7
	v_cvt_pk_bf16_f32 v21, v8, v9
	global_store_dwordx2 v[24:25], v[20:21], off
	s_waitcnt vmcnt(29)
	v_pk_fma_f32 v[8:9], v[8:9], v[100:101], v[42:43] op_sel_hi:[1,0,1]
	v_pk_fma_f32 v[6:7], v[6:7], v[100:101], v[40:41] op_sel_hi:[1,0,1]
	v_cmp_gt_u32_e64 s[4:5], v12, 3
	s_and_b64 exec, exec, s[4:5]
	s_cbranch_execz .Lscan_end
	v_lshlrev_b32_e32 v16, 15, v131
	v_lshl_add_u64 v[24:25], v[4:5], 0, v[16:17]
	v_cvt_pk_bf16_f32 v20, v6, v7
	v_cvt_pk_bf16_f32 v21, v8, v9
	global_store_dwordx2 v[24:25], v[20:21], off
	s_waitcnt vmcnt(28)
	v_pk_fma_f32 v[8:9], v[8:9], v[102:103], v[46:47] op_sel_hi:[1,0,1]
	v_pk_fma_f32 v[6:7], v[6:7], v[102:103], v[44:45] op_sel_hi:[1,0,1]
	v_cmp_gt_u32_e64 s[4:5], v12, 4
	s_and_b64 exec, exec, s[4:5]
	s_cbranch_execz .Lscan_end
	v_lshlrev_b32_e32 v16, 15, v132
	v_lshl_add_u64 v[24:25], v[4:5], 0, v[16:17]
	v_cvt_pk_bf16_f32 v20, v6, v7
	v_cvt_pk_bf16_f32 v21, v8, v9
	global_store_dwordx2 v[24:25], v[20:21], off
	s_waitcnt vmcnt(27)
	v_pk_fma_f32 v[8:9], v[8:9], v[104:105], v[50:51] op_sel_hi:[1,0,1]
	v_pk_fma_f32 v[6:7], v[6:7], v[104:105], v[48:49] op_sel_hi:[1,0,1]
	v_cmp_gt_u32_e64 s[4:5], v12, 5
	s_and_b64 exec, exec, s[4:5]
	s_cbranch_execz .Lscan_end
	v_lshlrev_b32_e32 v16, 15, v133
	v_lshl_add_u64 v[24:25], v[4:5], 0, v[16:17]
	v_cvt_pk_bf16_f32 v20, v6, v7
	v_cvt_pk_bf16_f32 v21, v8, v9
	global_store_dwordx2 v[24:25], v[20:21], off
	s_waitcnt vmcnt(26)
	v_pk_fma_f32 v[8:9], v[8:9], v[106:107], v[54:55] op_sel_hi:[1,0,1]
	v_pk_fma_f32 v[6:7], v[6:7], v[106:107], v[52:53] op_sel_hi:[1,0,1]
	v_cmp_gt_u32_e64 s[4:5], v12, 6
	s_and_b64 exec, exec, s[4:5]
	s_cbranch_execz .Lscan_end
	v_lshlrev_b32_e32 v16, 15, v134
	v_lshl_add_u64 v[24:25], v[4:5], 0, v[16:17]
	v_cvt_pk_bf16_f32 v20, v6, v7
	v_cvt_pk_bf16_f32 v21, v8, v9
	global_store_dwordx2 v[24:25], v[20:21], off
	s_waitcnt vmcnt(25)
	v_pk_fma_f32 v[8:9], v[8:9], v[108:109], v[58:59] op_sel_hi:[1,0,1]
	v_pk_fma_f32 v[6:7], v[6:7], v[108:109], v[56:57] op_sel_hi:[1,0,1]
	v_cmp_gt_u32_e64 s[4:5], v12, 7
	s_and_b64 exec, exec, s[4:5]
	s_cbranch_execz .Lscan_end
	v_lshlrev_b32_e32 v16, 15, v135
	v_lshl_add_u64 v[24:25], v[4:5], 0, v[16:17]
	v_cvt_pk_bf16_f32 v20, v6, v7
	v_cvt_pk_bf16_f32 v21, v8, v9
	global_store_dwordx2 v[24:25], v[20:21], off
	s_waitcnt vmcnt(24)
	v_pk_fma_f32 v[8:9], v[8:9], v[110:111], v[62:63] op_sel_hi:[1,0,1]
	v_pk_fma_f32 v[6:7], v[6:7], v[110:111], v[60:61] op_sel_hi:[1,0,1]
	v_cmp_gt_u32_e64 s[4:5], v12, 8
	s_and_b64 exec, exec, s[4:5]
	s_cbranch_execz .Lscan_end
	v_lshlrev_b32_e32 v16, 15, v136
	v_lshl_add_u64 v[24:25], v[4:5], 0, v[16:17]
	v_cvt_pk_bf16_f32 v20, v6, v7
	v_cvt_pk_bf16_f32 v21, v8, v9
	global_store_dwordx2 v[24:25], v[20:21], off
	s_waitcnt vmcnt(23)
	v_pk_fma_f32 v[8:9], v[8:9], v[112:113], v[66:67] op_sel_hi:[1,0,1]
	v_pk_fma_f32 v[6:7], v[6:7], v[112:113], v[64:65] op_sel_hi:[1,0,1]
	v_cmp_gt_u32_e64 s[4:5], v12, 9
	s_and_b64 exec, exec, s[4:5]
	s_cbranch_execz .Lscan_end
	v_lshlrev_b32_e32 v16, 15, v137
	v_lshl_add_u64 v[24:25], v[4:5], 0, v[16:17]
	v_cvt_pk_bf16_f32 v20, v6, v7
	v_cvt_pk_bf16_f32 v21, v8, v9
	global_store_dwordx2 v[24:25], v[20:21], off
	s_waitcnt vmcnt(22)
	v_pk_fma_f32 v[8:9], v[8:9], v[114:115], v[70:71] op_sel_hi:[1,0,1]
	v_pk_fma_f32 v[6:7], v[6:7], v[114:115], v[68:69] op_sel_hi:[1,0,1]
	v_cmp_gt_u32_e64 s[4:5], v12, 10
	s_and_b64 exec, exec, s[4:5]
	s_cbranch_execz .Lscan_end
	v_lshlrev_b32_e32 v16, 15, v138
	v_lshl_add_u64 v[24:25], v[4:5], 0, v[16:17]
	v_cvt_pk_bf16_f32 v20, v6, v7
	v_cvt_pk_bf16_f32 v21, v8, v9
	global_store_dwordx2 v[24:25], v[20:21], off
	s_waitcnt vmcnt(21)
	v_pk_fma_f32 v[8:9], v[8:9], v[116:117], v[74:75] op_sel_hi:[1,0,1]
	v_pk_fma_f32 v[6:7], v[6:7], v[116:117], v[72:73] op_sel_hi:[1,0,1]
	v_cmp_gt_u32_e64 s[4:5], v12, 11
	s_and_b64 exec, exec, s[4:5]
	s_cbranch_execz .Lscan_end
	v_lshlrev_b32_e32 v16, 15, v139
	v_lshl_add_u64 v[24:25], v[4:5], 0, v[16:17]
	v_cvt_pk_bf16_f32 v20, v6, v7
	v_cvt_pk_bf16_f32 v21, v8, v9
	global_store_dwordx2 v[24:25], v[20:21], off
	s_waitcnt vmcnt(20)
	v_pk_fma_f32 v[8:9], v[8:9], v[118:119], v[78:79] op_sel_hi:[1,0,1]
	v_pk_fma_f32 v[6:7], v[6:7], v[118:119], v[76:77] op_sel_hi:[1,0,1]
	v_cmp_gt_u32_e64 s[4:5], v12, 12
	s_and_b64 exec, exec, s[4:5]
	s_cbranch_execz .Lscan_end
	v_lshlrev_b32_e32 v16, 15, v140
	v_lshl_add_u64 v[24:25], v[4:5], 0, v[16:17]
	v_cvt_pk_bf16_f32 v20, v6, v7
	v_cvt_pk_bf16_f32 v21, v8, v9
	global_store_dwordx2 v[24:25], v[20:21], off
	s_waitcnt vmcnt(19)
	v_pk_fma_f32 v[8:9], v[8:9], v[120:121], v[82:83] op_sel_hi:[1,0,1]
	v_pk_fma_f32 v[6:7], v[6:7], v[120:121], v[80:81] op_sel_hi:[1,0,1]
	v_cmp_gt_u32_e64 s[4:5], v12, 13
	s_and_b64 exec, exec, s[4:5]
	s_cbranch_execz .Lscan_end
	v_lshlrev_b32_e32 v16, 15, v141
	v_lshl_add_u64 v[24:25], v[4:5], 0, v[16:17]
	v_cvt_pk_bf16_f32 v20, v6, v7
	v_cvt_pk_bf16_f32 v21, v8, v9
	global_store_dwordx2 v[24:25], v[20:21], off
	s_waitcnt vmcnt(18)
	v_pk_fma_f32 v[8:9], v[8:9], v[122:123], v[86:87] op_sel_hi:[1,0,1]
	v_pk_fma_f32 v[6:7], v[6:7], v[122:123], v[84:85] op_sel_hi:[1,0,1]
	v_cmp_gt_u32_e64 s[4:5], v12, 14
	s_and_b64 exec, exec, s[4:5]
	s_cbranch_execz .Lscan_end
	v_lshlrev_b32_e32 v16, 15, v142
	v_lshl_add_u64 v[24:25], v[4:5], 0, v[16:17]
	v_cvt_pk_bf16_f32 v20, v6, v7
	v_cvt_pk_bf16_f32 v21, v8, v9
	global_store_dwordx2 v[24:25], v[20:21], off
	s_waitcnt vmcnt(17)
	v_pk_fma_f32 v[8:9], v[8:9], v[124:125], v[90:91] op_sel_hi:[1,0,1]
	v_pk_fma_f32 v[6:7], v[6:7], v[124:125], v[88:89] op_sel_hi:[1,0,1]
	v_cmp_gt_u32_e64 s[4:5], v12, 15
	s_and_b64 exec, exec, s[4:5]
	s_cbranch_execz .Lscan_end
	v_lshlrev_b32_e32 v16, 15, v143
	v_lshl_add_u64 v[24:25], v[4:5], 0, v[16:17]
	v_cvt_pk_bf16_f32 v20, v6, v7
	v_cvt_pk_bf16_f32 v21, v8, v9
	global_store_dwordx2 v[24:25], v[20:21], off
	s_waitcnt vmcnt(16)
	v_pk_fma_f32 v[8:9], v[8:9], v[126:127], v[94:95] op_sel_hi:[1,0,1]
	v_pk_fma_f32 v[6:7], v[6:7], v[126:127], v[92:93] op_sel_hi:[1,0,1]
.Lscan_end:
	s_or_b64 exec, exec, s[14:15]
	v_add_u32_e32 v10, s96, v10
	v_cmp_lt_i32_e32 vcc, s0, v10
	s_or_b64 s[12:13], vcc, s[12:13]
	s_andn2_b64 exec, exec, s[12:13]
	s_cbranch_execnz .LBB0_420
